# cyclic K start per XCD (blockIdx & 7) instead of blockIdx & 31 in the hand-written big-tile GEMMs of phases 1, 10 and 13
# speedup vs baseline: 1.0155x; 1.0078x over previous
.LBB0_116:
	s_or_b64 exec, exec, s[0:1]
	s_add_u32 s0, s94, 0x15000000
	s_addc_u32 s1, s95, 0
	s_add_u32 s28, s94, 0x6c00000
	v_writelane_b32 v242, s0, 50
	s_addc_u32 s29, s95, 0
	v_mov_b32_e32 v0, v199
	v_writelane_b32 v242, s1, 51
	s_add_u32 s0, s94, 0xd000000
	s_addc_u32 s1, s95, 0
	v_writelane_b32 v242, s0, 52
	s_barrier
	s_nop 0
	v_writelane_b32 v242, s1, 53
	s_nop 0
	v_readlane_b32 s0, v242, 45
	v_readlane_b32 s1, v242, 46
	s_cmpk_gt_i32 s0, 0x29ff
	v_writelane_b32 v242, s58, 54
	s_nop 1
	v_writelane_b32 v242, s59, 55
	s_cbranch_scc1 .LBB0_246
	s_mov_b32 s91, 0
	s_cmp_lg_u32 s96, 0x200
	s_cbranch_scc1 .Lbig_skip
	v_lshrrev_b32_e32 v236, 3, v199
	v_lshrrev_b32_e32 v237, 4, v199
	v_xor_b32_e32 v237, v237, v199
	v_and_b32_e32 v237, 7, v237
	v_lshlrev_b32_e32 v237, 4, v237
	v_lshl_add_u32 v192, v236, 12, v237
	v_add_u32_e32 v193, 0x20000, v192
	v_add_u32_e32 v194, 0x40000, v192
	v_add_u32_e32 v195, 0x60000, v192
	v_and_b32_e32 v236, 15, v199
	v_bfe_u32 v237, v199, 4, 2
	v_lshrrev_b32_e32 v238, 1, v236
	v_lshlrev_b32_e32 v202, 3, v237
	v_xor_b32_e32 v237, v237, v238
	v_lshlrev_b32_e32 v237, 4, v237
	v_xor_b32_e32 v238, 64, v237
	v_lshrrev_b32_e32 v201, 7, v199
	v_lshl_add_u32 v201, v201, 7, v236
	v_lshlrev_b32_e32 v196, 7, v201
	v_bfe_u32 v198, v199, 6, 1
	v_lshl_add_u32 v202, v198, 7, v202
	v_lshl_add_u32 v198, v198, 6, v236
	v_lshlrev_b32_e32 v198, 7, v198
	v_add_u32_e32 v198, 0x8000, v198
	v_add_u32_e32 v197, v196, v238
	v_add_u32_e32 v200, v198, v238
	v_add_u32_e32 v196, v196, v237
	v_add_u32_e32 v198, v198, v237
	v_lshrrev_b32_e32 v236, 6, v199
	v_lshlrev_b32_e32 v236, 10, v236
	s_nop 0
	v_readfirstlane_b32 s32, v236
	v_lshrrev_b32_e32 v240, 6, v199
	v_mul_u32_u24_e32 v240, 0x900, v240
	v_add_u32_e32 v240, 0xc000, v240
	v_and_b32_e32 v241, 15, v199
	v_mul_u32_u24_e32 v241, 0x90, v241
	v_bfe_u32 v238, v199, 4, 2
	v_lshl_add_u32 v241, v238, 3, v241
	v_add_u32_e32 v236, v240, v241
	v_and_b32_e32 v241, 63, v199
	v_lshrrev_b32_e32 v238, 3, v241
	v_mul_u32_u24_e32 v238, 0x90, v238
	v_and_b32_e32 v241, 7, v241
	v_lshl_add_u32 v238, v241, 4, v238
	v_add_u32_e32 v237, v240, v238
	v_readlane_b32 s90, v242, 45
	s_and_b32 s51, s90, 63
	s_lshl_b32 s51, s51, 20
	s_add_u32 s36, s94, s51
	s_addc_u32 s37, s95, 0
	s_add_u32 s36, s36, 0x15000000
	s_addc_u32 s37, s37, 0
	s_lshr_b32 s51, s90, 6
	s_lshl_b32 s51, s51, 19
	s_add_u32 s44, s94, s51
	s_addc_u32 s45, s95, 0
	s_add_u32 s44, s44, 0x19000000
	s_addc_u32 s45, s45, 0
	s_add_u32 s40, s36, 0x80000
	s_addc_u32 s41, s37, 0
	s_and_b32 s21, s90, 7
	s_lshl_b32 s21, s21, 2
	s_mov_b32 s20, s21
	s_lshl_b32 s51, s21, 7
	s_add_u32 s36, s36, s51
	s_addc_u32 s37, s37, 0
	s_add_u32 s40, s40, s51
	s_addc_u32 s41, s41, 0
	s_add_u32 s44, s44, s51
	s_addc_u32 s45, s45, 0
	s_barrier
	s_add_u32 m0, s32, 0x0
	s_nop 0
	global_load_lds_dwordx4 v192, s[36:37]
	s_add_u32 m0, s32, 0x1000
	s_nop 0
	global_load_lds_dwordx4 v193, s[36:37]
	s_add_u32 m0, s32, 0x2000
	s_nop 0
	global_load_lds_dwordx4 v194, s[36:37]
	s_add_u32 m0, s32, 0x3000
	s_nop 0
	global_load_lds_dwordx4 v195, s[36:37]
	s_add_u32 m0, s32, 0x4000
	s_nop 0
	global_load_lds_dwordx4 v192, s[40:41]
	s_add_u32 m0, s32, 0x5000
	s_nop 0
	global_load_lds_dwordx4 v193, s[40:41]
	s_add_u32 m0, s32, 0x6000
	s_nop 0
	global_load_lds_dwordx4 v194, s[40:41]
	s_add_u32 m0, s32, 0x7000
	s_nop 0
	global_load_lds_dwordx4 v195, s[40:41]
	s_add_u32 m0, s32, 0x8000
	s_nop 0
	global_load_lds_dwordx4 v192, s[44:45]
	s_add_u32 m0, s32, 0x9000
	s_nop 0
	global_load_lds_dwordx4 v193, s[44:45]
	s_add_u32 m0, s32, 0xa000
	s_nop 0
	global_load_lds_dwordx4 v194, s[44:45]
	s_add_u32 m0, s32, 0xb000
	s_nop 0
	global_load_lds_dwordx4 v195, s[44:45]
	s_add_u32 s36, s36, 0x80
	s_addc_u32 s37, s37, 0
	s_add_u32 s40, s40, 0x80
	s_addc_u32 s41, s41, 0
	s_add_u32 s44, s44, 0x80
	s_addc_u32 s45, s45, 0
	s_add_i32 s20, s20, 1
	s_cmp_eq_u32 s20, 32
	s_cbranch_scc1 .Lbig_wrap0

.LBB0_763:
	s_or_b64 exec, exec, s[0:1]
	s_mov_b32 s91, 0
	s_cmp_lg_u32 s96, 0x200
	s_cbranch_scc1 .Lq10_skip
	v_lshrrev_b32_e32 v236, 3, v199
	v_lshrrev_b32_e32 v237, 4, v199
	v_xor_b32_e32 v237, v237, v199
	v_and_b32_e32 v237, 7, v237
	v_lshlrev_b32_e32 v237, 4, v237
	v_lshl_add_u32 v192, v236, 12, v237
	v_add_u32_e32 v193, 0x20000, v192
	v_add_u32_e32 v194, 0x40000, v192
	v_add_u32_e32 v195, 0x60000, v192
	v_and_b32_e32 v236, 15, v199
	v_bfe_u32 v237, v199, 4, 2
	v_lshrrev_b32_e32 v238, 1, v236
	v_lshlrev_b32_e32 v202, 3, v237
	v_xor_b32_e32 v237, v237, v238
	v_lshlrev_b32_e32 v237, 4, v237
	v_xor_b32_e32 v238, 64, v237
	v_lshrrev_b32_e32 v201, 7, v199
	v_lshl_add_u32 v201, v201, 7, v236
	v_lshlrev_b32_e32 v196, 7, v201
	v_bfe_u32 v198, v199, 6, 1
	v_lshl_add_u32 v202, v198, 7, v202
	v_lshl_add_u32 v198, v198, 6, v236
	v_lshlrev_b32_e32 v198, 7, v198
	v_add_u32_e32 v198, 0x8000, v198
	v_add_u32_e32 v197, v196, v238
	v_add_u32_e32 v243, v198, v238
	v_add_u32_e32 v196, v196, v237
	v_add_u32_e32 v198, v198, v237
	v_lshrrev_b32_e32 v236, 6, v199
	v_lshlrev_b32_e32 v236, 10, v236
	s_nop 0
	v_readfirstlane_b32 s32, v236
	v_lshrrev_b32_e32 v240, 6, v199
	v_mul_u32_u24_e32 v240, 0x900, v240
	v_add_u32_e32 v240, 0xc000, v240
	v_and_b32_e32 v241, 15, v199
	v_mul_u32_u24_e32 v241, 0x90, v241
	v_bfe_u32 v238, v199, 4, 2
	v_lshl_add_u32 v241, v238, 3, v241
	v_add_u32_e32 v236, v240, v241
	v_and_b32_e32 v241, 63, v199
	v_lshrrev_b32_e32 v238, 3, v241
	v_mul_u32_u24_e32 v238, 0x90, v238
	v_and_b32_e32 v241, 7, v241
	v_lshl_add_u32 v238, v241, 4, v238
	v_add_u32_e32 v237, v240, v238
	v_readlane_b32 s90, v242, 45
	s_and_b32 s51, s90, 63
	s_lshl_b32 s51, s51, 20
	s_add_u32 s36, s94, s51
	s_addc_u32 s37, s95, 0
	s_add_u32 s36, s36, 0x15000000
	s_addc_u32 s37, s37, 0
	s_lshr_b32 s51, s90, 6
	s_lshl_b32 s51, s51, 19
	s_add_u32 s44, s94, s51
	s_addc_u32 s45, s95, 0
	s_add_u32 s44, s44, 0x1c200000
	s_addc_u32 s45, s45, 0
	s_add_u32 s40, s36, 0x80000
	s_addc_u32 s41, s37, 0
	s_and_b32 s21, s90, 7
	s_lshl_b32 s21, s21, 2
	s_mov_b32 s20, s21
	s_lshl_b32 s51, s21, 7
	s_add_u32 s36, s36, s51
	s_addc_u32 s37, s37, 0
	s_add_u32 s40, s40, s51
	s_addc_u32 s41, s41, 0
	s_add_u32 s44, s44, s51
	s_addc_u32 s45, s45, 0
	s_barrier
	s_add_u32 m0, s32, 0x0
	s_nop 0
	global_load_lds_dwordx4 v192, s[36:37]
	s_add_u32 m0, s32, 0x1000
	s_nop 0
	global_load_lds_dwordx4 v193, s[36:37]
	s_add_u32 m0, s32, 0x2000
	s_nop 0
	global_load_lds_dwordx4 v194, s[36:37]
	s_add_u32 m0, s32, 0x3000
	s_nop 0
	global_load_lds_dwordx4 v195, s[36:37]
	s_add_u32 m0, s32, 0x4000
	s_nop 0
	global_load_lds_dwordx4 v192, s[40:41]
	s_add_u32 m0, s32, 0x5000
	s_nop 0
	global_load_lds_dwordx4 v193, s[40:41]
	s_add_u32 m0, s32, 0x6000
	s_nop 0
	global_load_lds_dwordx4 v194, s[40:41]
	s_add_u32 m0, s32, 0x7000
	s_nop 0
	global_load_lds_dwordx4 v195, s[40:41]
	s_add_u32 m0, s32, 0x8000
	s_nop 0
	global_load_lds_dwordx4 v192, s[44:45]
	s_add_u32 m0, s32, 0x9000
	s_nop 0
	global_load_lds_dwordx4 v193, s[44:45]
	s_add_u32 m0, s32, 0xa000
	s_nop 0
	global_load_lds_dwordx4 v194, s[44:45]
	s_add_u32 m0, s32, 0xb000
	s_nop 0
	global_load_lds_dwordx4 v195, s[44:45]
	s_add_u32 s36, s36, 0x80
	s_addc_u32 s37, s37, 0
	s_add_u32 s40, s40, 0x80
	s_addc_u32 s41, s41, 0
	s_add_u32 s44, s44, 0x80
	s_addc_u32 s45, s45, 0
	s_add_i32 s20, s20, 1
	s_cmp_eq_u32 s20, 32
	s_cbranch_scc1 .Lq10_wrap0

.Lple_tile:
	s_and_b32 s28, s29, 63
	s_lshl_b32 s28, s28, 17
	s_add_u32 s40, s94, s28
	s_addc_u32 s41, s95, 0
	s_add_u32 s40, s40, 0x1d3a0000
	s_addc_u32 s41, s41, 0
	s_add_u32 s42, s40, 0x10000
	s_addc_u32 s43, s41, 0
	s_lshr_b32 s28, s29, 6
	s_lshl_b32 s28, s28, 16
	s_add_u32 s44, s94, s28
	s_addc_u32 s45, s95, 0
	s_add_u32 s44, s44, 0x1d200000
	s_addc_u32 s45, s45, 0
	s_mov_b32 s46, 0x180
	v_readlane_b32 s39, v242, 45
	s_and_b32 s39, s39, 7
	s_lshl_b32 s39, s39, 9
	s_and_b32 s39, s39, s46
	s_add_u32 s20, s40, s39
	s_addc_u32 s21, s41, 0
	s_add_u32 s22, s42, s39
	s_addc_u32 s23, s43, 0
	s_add_u32 s24, s44, s39
	s_addc_u32 s25, s45, 0
	s_barrier
	s_add_u32 m0, s26, 0x0
	s_nop 0
	global_load_lds_dwordx4 v192, s[20:21]
	s_add_u32 m0, s26, 0x1000
	s_nop 0
	global_load_lds_dwordx4 v193, s[20:21]
	s_add_u32 m0, s26, 0x2000
	s_nop 0
	global_load_lds_dwordx4 v194, s[20:21]
	s_add_u32 m0, s26, 0x3000
	s_nop 0
	global_load_lds_dwordx4 v195, s[20:21]
	s_add_u32 m0, s26, 0x4000
	s_nop 0
	global_load_lds_dwordx4 v192, s[22:23]
	s_add_u32 m0, s26, 0x5000
	s_nop 0
	global_load_lds_dwordx4 v193, s[22:23]
	s_add_u32 m0, s26, 0x6000
	s_nop 0
	global_load_lds_dwordx4 v194, s[22:23]
	s_add_u32 m0, s26, 0x7000
	s_nop 0
	global_load_lds_dwordx4 v195, s[22:23]
	s_add_u32 m0, s26, 0x8000
	s_nop 0
	global_load_lds_dwordx4 v192, s[24:25]
	s_add_u32 m0, s26, 0x9000
	s_nop 0
	global_load_lds_dwordx4 v193, s[24:25]
	s_add_u32 m0, s26, 0xa000
	s_nop 0
	global_load_lds_dwordx4 v194, s[24:25]
	s_add_u32 m0, s26, 0xb000
	s_nop 0
	global_load_lds_dwordx4 v195, s[24:25]
	s_add_u32 s39, s39, 0x80
	s_and_b32 s39, s39, s46
	s_add_u32 s20, s40, s39
	s_addc_u32 s21, s41, 0
	s_add_u32 s22, s42, s39
	s_addc_u32 s23, s43, 0
	s_add_u32 s24, s44, s39
	s_addc_u32 s25, s45, 0
	v_mov_b32_e32 v0, 0
	v_mov_b32_e32 v1, 0
	v_mov_b32_e32 v2, 0
	v_mov_b32_e32 v3, 0
	v_mov_b32_e32 v4, 0
	v_mov_b32_e32 v5, 0
	v_mov_b32_e32 v6, 0
	v_mov_b32_e32 v7, 0
	v_mov_b32_e32 v8, 0
	v_mov_b32_e32 v9, 0
	v_mov_b32_e32 v10, 0
	v_mov_b32_e32 v11, 0
	v_mov_b32_e32 v12, 0
	v_mov_b32_e32 v13, 0
	v_mov_b32_e32 v14, 0
	v_mov_b32_e32 v15, 0
	v_mov_b32_e32 v16, 0
	v_mov_b32_e32 v17, 0
	v_mov_b32_e32 v18, 0
	v_mov_b32_e32 v19, 0
	v_mov_b32_e32 v20, 0
	v_mov_b32_e32 v21, 0
	v_mov_b32_e32 v22, 0
	v_mov_b32_e32 v23, 0
	v_mov_b32_e32 v24, 0
	v_mov_b32_e32 v25, 0
	v_mov_b32_e32 v26, 0
	v_mov_b32_e32 v27, 0
	v_mov_b32_e32 v28, 0
	v_mov_b32_e32 v29, 0
	v_mov_b32_e32 v30, 0
	v_mov_b32_e32 v31, 0
	v_mov_b32_e32 v32, 0
	v_mov_b32_e32 v33, 0
	v_mov_b32_e32 v34, 0
	v_mov_b32_e32 v35, 0
	v_mov_b32_e32 v36, 0
	v_mov_b32_e32 v37, 0
	v_mov_b32_e32 v38, 0
	v_mov_b32_e32 v39, 0
	v_mov_b32_e32 v40, 0
	v_mov_b32_e32 v41, 0
	v_mov_b32_e32 v42, 0
	v_mov_b32_e32 v43, 0
	v_mov_b32_e32 v44, 0
	v_mov_b32_e32 v45, 0
	v_mov_b32_e32 v46, 0
	v_mov_b32_e32 v47, 0
	v_mov_b32_e32 v48, 0
	v_mov_b32_e32 v49, 0
	v_mov_b32_e32 v50, 0
	v_mov_b32_e32 v51, 0
	v_mov_b32_e32 v52, 0
	v_mov_b32_e32 v53, 0
	v_mov_b32_e32 v54, 0
	v_mov_b32_e32 v55, 0
	v_mov_b32_e32 v56, 0
	v_mov_b32_e32 v57, 0
	v_mov_b32_e32 v58, 0
	v_mov_b32_e32 v59, 0
	v_mov_b32_e32 v60, 0
	v_mov_b32_e32 v61, 0
	v_mov_b32_e32 v62, 0
	v_mov_b32_e32 v63, 0
	v_mov_b32_e32 v64, 0
	v_mov_b32_e32 v65, 0
	v_mov_b32_e32 v66, 0
	v_mov_b32_e32 v67, 0
	v_mov_b32_e32 v68, 0
	v_mov_b32_e32 v69, 0
	v_mov_b32_e32 v70, 0
	v_mov_b32_e32 v71, 0
	v_mov_b32_e32 v72, 0
	v_mov_b32_e32 v73, 0
	v_mov_b32_e32 v74, 0
	v_mov_b32_e32 v75, 0
	v_mov_b32_e32 v76, 0
	v_mov_b32_e32 v77, 0
	v_mov_b32_e32 v78, 0
	v_mov_b32_e32 v79, 0
	v_mov_b32_e32 v80, 0
	v_mov_b32_e32 v81, 0
	v_mov_b32_e32 v82, 0
	v_mov_b32_e32 v83, 0
	v_mov_b32_e32 v84, 0
	v_mov_b32_e32 v85, 0
	v_mov_b32_e32 v86, 0
	v_mov_b32_e32 v87, 0
	v_mov_b32_e32 v88, 0
	v_mov_b32_e32 v89, 0
	v_mov_b32_e32 v90, 0
	v_mov_b32_e32 v91, 0
	v_mov_b32_e32 v92, 0
	v_mov_b32_e32 v93, 0
	v_mov_b32_e32 v94, 0
	v_mov_b32_e32 v95, 0
	v_mov_b32_e32 v96, 0
	v_mov_b32_e32 v97, 0
	v_mov_b32_e32 v98, 0
	v_mov_b32_e32 v99, 0
	v_mov_b32_e32 v100, 0
	v_mov_b32_e32 v101, 0
	v_mov_b32_e32 v102, 0
	v_mov_b32_e32 v103, 0
	v_mov_b32_e32 v104, 0
	v_mov_b32_e32 v105, 0
	v_mov_b32_e32 v106, 0
	v_mov_b32_e32 v107, 0
	v_mov_b32_e32 v108, 0
	v_mov_b32_e32 v109, 0
	v_mov_b32_e32 v110, 0
	v_mov_b32_e32 v111, 0
	v_mov_b32_e32 v112, 0
	v_mov_b32_e32 v113, 0
	v_mov_b32_e32 v114, 0
	v_mov_b32_e32 v115, 0
	v_mov_b32_e32 v116, 0
	v_mov_b32_e32 v117, 0
	v_mov_b32_e32 v118, 0
	v_mov_b32_e32 v119, 0
	v_mov_b32_e32 v120, 0
	v_mov_b32_e32 v121, 0
	v_mov_b32_e32 v122, 0
	v_mov_b32_e32 v123, 0
	v_mov_b32_e32 v124, 0
	v_mov_b32_e32 v125, 0
	v_mov_b32_e32 v126, 0
	v_mov_b32_e32 v127, 0
	s_mov_b32 s27, 0
.Lple_ka:
	s_waitcnt vmcnt(0)
	s_barrier
	ds_read_b128 v[160:163], v198 offset:0
	ds_read_b128 v[164:167], v198 offset:2048
	ds_read_b128 v[168:171], v198 offset:4096
	ds_read_b128 v[172:175], v198 offset:6144
	ds_read_b128 v[128:131], v196 offset:0
	ds_read_b128 v[132:135], v196 offset:2048
	ds_read_b128 v[136:139], v196 offset:4096
	ds_read_b128 v[140:143], v196 offset:6144
	ds_read_b128 v[144:147], v196 offset:8192
	ds_read_b128 v[148:151], v196 offset:10240
	ds_read_b128 v[152:155], v196 offset:12288
	ds_read_b128 v[156:159], v196 offset:14336
	ds_read_b128 v[176:179], v241 offset:0
	ds_read_b128 v[180:183], v241 offset:2048
	ds_read_b128 v[184:187], v241 offset:4096
	ds_read_b128 v[188:191], v241 offset:6144
	ds_read_b128 v[204:207], v197 offset:0
	ds_read_b128 v[208:211], v197 offset:2048
	ds_read_b128 v[212:215], v197 offset:4096
	ds_read_b128 v[216:219], v197 offset:6144
	ds_read_b128 v[220:223], v197 offset:8192
	ds_read_b128 v[224:227], v197 offset:10240
	ds_read_b128 v[228:231], v197 offset:12288
	ds_read_b128 v[232:235], v197 offset:14336
	s_setprio 1
	s_waitcnt lgkmcnt(15)
	v_mfma_f32_16x16x32_bf16 v[0:3], v[160:163], v[128:131], v[0:3]
	v_mfma_f32_16x16x32_bf16 v[4:7], v[164:167], v[128:131], v[4:7]
	v_mfma_f32_16x16x32_bf16 v[8:11], v[168:171], v[128:131], v[8:11]
	v_mfma_f32_16x16x32_bf16 v[12:15], v[172:175], v[128:131], v[12:15]
	s_waitcnt lgkmcnt(15)
	v_mfma_f32_16x16x32_bf16 v[16:19], v[160:163], v[132:135], v[16:19]
	v_mfma_f32_16x16x32_bf16 v[20:23], v[164:167], v[132:135], v[20:23]
	v_mfma_f32_16x16x32_bf16 v[24:27], v[168:171], v[132:135], v[24:27]
	v_mfma_f32_16x16x32_bf16 v[28:31], v[172:175], v[132:135], v[28:31]
	s_waitcnt lgkmcnt(15)
	v_mfma_f32_16x16x32_bf16 v[32:35], v[160:163], v[136:139], v[32:35]
	v_mfma_f32_16x16x32_bf16 v[36:39], v[164:167], v[136:139], v[36:39]
	v_mfma_f32_16x16x32_bf16 v[40:43], v[168:171], v[136:139], v[40:43]
	v_mfma_f32_16x16x32_bf16 v[44:47], v[172:175], v[136:139], v[44:47]
	s_waitcnt lgkmcnt(15)
	v_mfma_f32_16x16x32_bf16 v[48:51], v[160:163], v[140:143], v[48:51]
	v_mfma_f32_16x16x32_bf16 v[52:55], v[164:167], v[140:143], v[52:55]
	v_mfma_f32_16x16x32_bf16 v[56:59], v[168:171], v[140:143], v[56:59]
	v_mfma_f32_16x16x32_bf16 v[60:63], v[172:175], v[140:143], v[60:63]
	s_waitcnt lgkmcnt(15)
	v_mfma_f32_16x16x32_bf16 v[64:67], v[160:163], v[144:147], v[64:67]
	v_mfma_f32_16x16x32_bf16 v[68:71], v[164:167], v[144:147], v[68:71]
	v_mfma_f32_16x16x32_bf16 v[72:75], v[168:171], v[144:147], v[72:75]
	v_mfma_f32_16x16x32_bf16 v[76:79], v[172:175], v[144:147], v[76:79]
	s_waitcnt lgkmcnt(14)
	v_mfma_f32_16x16x32_bf16 v[80:83], v[160:163], v[148:151], v[80:83]
	v_mfma_f32_16x16x32_bf16 v[84:87], v[164:167], v[148:151], v[84:87]
	v_mfma_f32_16x16x32_bf16 v[88:91], v[168:171], v[148:151], v[88:91]
	v_mfma_f32_16x16x32_bf16 v[92:95], v[172:175], v[148:151], v[92:95]
	s_waitcnt lgkmcnt(13)
	v_mfma_f32_16x16x32_bf16 v[96:99], v[160:163], v[152:155], v[96:99]
	v_mfma_f32_16x16x32_bf16 v[100:103], v[164:167], v[152:155], v[100:103]
	v_mfma_f32_16x16x32_bf16 v[104:107], v[168:171], v[152:155], v[104:107]
	v_mfma_f32_16x16x32_bf16 v[108:111], v[172:175], v[152:155], v[108:111]
	s_waitcnt lgkmcnt(12)
	v_mfma_f32_16x16x32_bf16 v[112:115], v[160:163], v[156:159], v[112:115]
	v_mfma_f32_16x16x32_bf16 v[116:119], v[164:167], v[156:159], v[116:119]
	v_mfma_f32_16x16x32_bf16 v[120:123], v[168:171], v[156:159], v[120:123]
	v_mfma_f32_16x16x32_bf16 v[124:127], v[172:175], v[156:159], v[124:127]
	s_setprio 0
	s_waitcnt lgkmcnt(0)
	s_barrier
	s_add_u32 m0, s26, 0x0
	s_nop 0
	global_load_lds_dwordx4 v192, s[20:21]
	s_add_u32 m0, s26, 0x1000
	s_nop 0
	global_load_lds_dwordx4 v193, s[20:21]
	s_add_u32 m0, s26, 0x2000
	s_nop 0
	global_load_lds_dwordx4 v194, s[20:21]
	s_add_u32 m0, s26, 0x3000
	s_nop 0
	global_load_lds_dwordx4 v195, s[20:21]
	s_add_u32 m0, s26, 0x4000
	s_nop 0
	global_load_lds_dwordx4 v192, s[22:23]
	s_add_u32 m0, s26, 0x5000
	s_nop 0
	global_load_lds_dwordx4 v193, s[22:23]
	s_add_u32 m0, s26, 0x6000
	s_nop 0
	global_load_lds_dwordx4 v194, s[22:23]
	s_add_u32 m0, s26, 0x7000
	s_nop 0
	global_load_lds_dwordx4 v195, s[22:23]
	s_add_u32 m0, s26, 0x8000
	s_nop 0
	global_load_lds_dwordx4 v192, s[24:25]
	s_add_u32 m0, s26, 0x9000
	s_nop 0
	global_load_lds_dwordx4 v193, s[24:25]
	s_add_u32 m0, s26, 0xa000
	s_nop 0
	global_load_lds_dwordx4 v194, s[24:25]
	s_add_u32 m0, s26, 0xb000
	s_nop 0
	global_load_lds_dwordx4 v195, s[24:25]
	s_add_u32 s39, s39, 0x80
	s_and_b32 s39, s39, s46
	s_add_u32 s20, s40, s39
	s_addc_u32 s21, s41, 0
	s_add_u32 s22, s42, s39
	s_addc_u32 s23, s43, 0
	s_add_u32 s24, s44, s39
	s_addc_u32 s25, s45, 0
	s_setprio 1
	v_mfma_f32_16x16x32_bf16 v[0:3], v[176:179], v[204:207], v[0:3]
	v_mfma_f32_16x16x32_bf16 v[4:7], v[180:183], v[204:207], v[4:7]
	v_mfma_f32_16x16x32_bf16 v[8:11], v[184:187], v[204:207], v[8:11]
	v_mfma_f32_16x16x32_bf16 v[12:15], v[188:191], v[204:207], v[12:15]
	v_mfma_f32_16x16x32_bf16 v[16:19], v[176:179], v[208:211], v[16:19]
	v_mfma_f32_16x16x32_bf16 v[20:23], v[180:183], v[208:211], v[20:23]
	v_mfma_f32_16x16x32_bf16 v[24:27], v[184:187], v[208:211], v[24:27]
	v_mfma_f32_16x16x32_bf16 v[28:31], v[188:191], v[208:211], v[28:31]
	v_mfma_f32_16x16x32_bf16 v[32:35], v[176:179], v[212:215], v[32:35]
	v_mfma_f32_16x16x32_bf16 v[36:39], v[180:183], v[212:215], v[36:39]
	v_mfma_f32_16x16x32_bf16 v[40:43], v[184:187], v[212:215], v[40:43]
	v_mfma_f32_16x16x32_bf16 v[44:47], v[188:191], v[212:215], v[44:47]
	v_mfma_f32_16x16x32_bf16 v[48:51], v[176:179], v[216:219], v[48:51]
	v_mfma_f32_16x16x32_bf16 v[52:55], v[180:183], v[216:219], v[52:55]
	v_mfma_f32_16x16x32_bf16 v[56:59], v[184:187], v[216:219], v[56:59]
	v_mfma_f32_16x16x32_bf16 v[60:63], v[188:191], v[216:219], v[60:63]
	v_mfma_f32_16x16x32_bf16 v[64:67], v[176:179], v[220:223], v[64:67]
	v_mfma_f32_16x16x32_bf16 v[68:71], v[180:183], v[220:223], v[68:71]
	v_mfma_f32_16x16x32_bf16 v[72:75], v[184:187], v[220:223], v[72:75]
	v_mfma_f32_16x16x32_bf16 v[76:79], v[188:191], v[220:223], v[76:79]
	v_mfma_f32_16x16x32_bf16 v[80:83], v[176:179], v[224:227], v[80:83]
	v_mfma_f32_16x16x32_bf16 v[84:87], v[180:183], v[224:227], v[84:87]
	v_mfma_f32_16x16x32_bf16 v[88:91], v[184:187], v[224:227], v[88:91]
	v_mfma_f32_16x16x32_bf16 v[92:95], v[188:191], v[224:227], v[92:95]
	v_mfma_f32_16x16x32_bf16 v[96:99], v[176:179], v[228:231], v[96:99]
	v_mfma_f32_16x16x32_bf16 v[100:103], v[180:183], v[228:231], v[100:103]
	v_mfma_f32_16x16x32_bf16 v[104:107], v[184:187], v[228:231], v[104:107]
	v_mfma_f32_16x16x32_bf16 v[108:111], v[188:191], v[228:231], v[108:111]
	v_mfma_f32_16x16x32_bf16 v[112:115], v[176:179], v[232:235], v[112:115]
	v_mfma_f32_16x16x32_bf16 v[116:119], v[180:183], v[232:235], v[116:119]
	v_mfma_f32_16x16x32_bf16 v[120:123], v[184:187], v[232:235], v[120:123]
	v_mfma_f32_16x16x32_bf16 v[124:127], v[188:191], v[232:235], v[124:127]
	s_setprio 0
	s_add_i32 s27, s27, 1
	s_cmp_lt_u32 s27, 3
	s_cbranch_scc1 .Lple_ka
	s_waitcnt vmcnt(0)
	s_barrier
	ds_read_b128 v[160:163], v198 offset:0
	ds_read_b128 v[164:167], v198 offset:2048
	ds_read_b128 v[168:171], v198 offset:4096
	ds_read_b128 v[172:175], v198 offset:6144
	ds_read_b128 v[128:131], v196 offset:0
	ds_read_b128 v[132:135], v196 offset:2048
	ds_read_b128 v[136:139], v196 offset:4096
	ds_read_b128 v[140:143], v196 offset:6144
	ds_read_b128 v[144:147], v196 offset:8192
	ds_read_b128 v[148:151], v196 offset:10240
	ds_read_b128 v[152:155], v196 offset:12288
	ds_read_b128 v[156:159], v196 offset:14336
	ds_read_b128 v[176:179], v241 offset:0
	ds_read_b128 v[180:183], v241 offset:2048
	ds_read_b128 v[184:187], v241 offset:4096
	ds_read_b128 v[188:191], v241 offset:6144
	ds_read_b128 v[204:207], v197 offset:0
	ds_read_b128 v[208:211], v197 offset:2048
	ds_read_b128 v[212:215], v197 offset:4096
	ds_read_b128 v[216:219], v197 offset:6144
	ds_read_b128 v[220:223], v197 offset:8192
	ds_read_b128 v[224:227], v197 offset:10240
	ds_read_b128 v[228:231], v197 offset:12288
	ds_read_b128 v[232:235], v197 offset:14336
	s_setprio 1
	s_waitcnt lgkmcnt(15)
	v_mfma_f32_16x16x32_bf16 v[0:3], v[160:163], v[128:131], v[0:3]
	v_mfma_f32_16x16x32_bf16 v[4:7], v[164:167], v[128:131], v[4:7]
	v_mfma_f32_16x16x32_bf16 v[8:11], v[168:171], v[128:131], v[8:11]
	v_mfma_f32_16x16x32_bf16 v[12:15], v[172:175], v[128:131], v[12:15]
	s_waitcnt lgkmcnt(15)
	v_mfma_f32_16x16x32_bf16 v[16:19], v[160:163], v[132:135], v[16:19]
	v_mfma_f32_16x16x32_bf16 v[20:23], v[164:167], v[132:135], v[20:23]
	v_mfma_f32_16x16x32_bf16 v[24:27], v[168:171], v[132:135], v[24:27]
	v_mfma_f32_16x16x32_bf16 v[28:31], v[172:175], v[132:135], v[28:31]
	s_waitcnt lgkmcnt(15)
	v_mfma_f32_16x16x32_bf16 v[32:35], v[160:163], v[136:139], v[32:35]
	v_mfma_f32_16x16x32_bf16 v[36:39], v[164:167], v[136:139], v[36:39]
	v_mfma_f32_16x16x32_bf16 v[40:43], v[168:171], v[136:139], v[40:43]
	v_mfma_f32_16x16x32_bf16 v[44:47], v[172:175], v[136:139], v[44:47]
	s_waitcnt lgkmcnt(15)
	v_mfma_f32_16x16x32_bf16 v[48:51], v[160:163], v[140:143], v[48:51]
	v_mfma_f32_16x16x32_bf16 v[52:55], v[164:167], v[140:143], v[52:55]
	v_mfma_f32_16x16x32_bf16 v[56:59], v[168:171], v[140:143], v[56:59]
	v_mfma_f32_16x16x32_bf16 v[60:63], v[172:175], v[140:143], v[60:63]
	s_waitcnt lgkmcnt(15)
	v_mfma_f32_16x16x32_bf16 v[64:67], v[160:163], v[144:147], v[64:67]
	v_mfma_f32_16x16x32_bf16 v[68:71], v[164:167], v[144:147], v[68:71]
	v_mfma_f32_16x16x32_bf16 v[72:75], v[168:171], v[144:147], v[72:75]
	v_mfma_f32_16x16x32_bf16 v[76:79], v[172:175], v[144:147], v[76:79]
	s_waitcnt lgkmcnt(14)
	v_mfma_f32_16x16x32_bf16 v[80:83], v[160:163], v[148:151], v[80:83]
	v_mfma_f32_16x16x32_bf16 v[84:87], v[164:167], v[148:151], v[84:87]
	v_mfma_f32_16x16x32_bf16 v[88:91], v[168:171], v[148:151], v[88:91]
	v_mfma_f32_16x16x32_bf16 v[92:95], v[172:175], v[148:151], v[92:95]
	s_waitcnt lgkmcnt(13)
	v_mfma_f32_16x16x32_bf16 v[96:99], v[160:163], v[152:155], v[96:99]
	v_mfma_f32_16x16x32_bf16 v[100:103], v[164:167], v[152:155], v[100:103]
	v_mfma_f32_16x16x32_bf16 v[104:107], v[168:171], v[152:155], v[104:107]
	v_mfma_f32_16x16x32_bf16 v[108:111], v[172:175], v[152:155], v[108:111]
	s_waitcnt lgkmcnt(12)
	v_mfma_f32_16x16x32_bf16 v[112:115], v[160:163], v[156:159], v[112:115]
	v_mfma_f32_16x16x32_bf16 v[116:119], v[164:167], v[156:159], v[116:119]
	v_mfma_f32_16x16x32_bf16 v[120:123], v[168:171], v[156:159], v[120:123]
	v_mfma_f32_16x16x32_bf16 v[124:127], v[172:175], v[156:159], v[124:127]
	s_setprio 0
	s_waitcnt lgkmcnt(0)
	s_setprio 1
	v_mfma_f32_16x16x32_bf16 v[0:3], v[176:179], v[204:207], v[0:3]
	v_mfma_f32_16x16x32_bf16 v[4:7], v[180:183], v[204:207], v[4:7]
	v_mfma_f32_16x16x32_bf16 v[8:11], v[184:187], v[204:207], v[8:11]
	v_mfma_f32_16x16x32_bf16 v[12:15], v[188:191], v[204:207], v[12:15]
	v_mfma_f32_16x16x32_bf16 v[16:19], v[176:179], v[208:211], v[16:19]
	v_mfma_f32_16x16x32_bf16 v[20:23], v[180:183], v[208:211], v[20:23]
	v_mfma_f32_16x16x32_bf16 v[24:27], v[184:187], v[208:211], v[24:27]
	v_mfma_f32_16x16x32_bf16 v[28:31], v[188:191], v[208:211], v[28:31]
	v_mfma_f32_16x16x32_bf16 v[32:35], v[176:179], v[212:215], v[32:35]
	v_mfma_f32_16x16x32_bf16 v[36:39], v[180:183], v[212:215], v[36:39]
	v_mfma_f32_16x16x32_bf16 v[40:43], v[184:187], v[212:215], v[40:43]
	v_mfma_f32_16x16x32_bf16 v[44:47], v[188:191], v[212:215], v[44:47]
	v_mfma_f32_16x16x32_bf16 v[48:51], v[176:179], v[216:219], v[48:51]
	v_mfma_f32_16x16x32_bf16 v[52:55], v[180:183], v[216:219], v[52:55]
	v_mfma_f32_16x16x32_bf16 v[56:59], v[184:187], v[216:219], v[56:59]
	v_mfma_f32_16x16x32_bf16 v[60:63], v[188:191], v[216:219], v[60:63]
	v_mfma_f32_16x16x32_bf16 v[64:67], v[176:179], v[220:223], v[64:67]
	v_mfma_f32_16x16x32_bf16 v[68:71], v[180:183], v[220:223], v[68:71]
	v_mfma_f32_16x16x32_bf16 v[72:75], v[184:187], v[220:223], v[72:75]
	v_mfma_f32_16x16x32_bf16 v[76:79], v[188:191], v[220:223], v[76:79]
	v_mfma_f32_16x16x32_bf16 v[80:83], v[176:179], v[224:227], v[80:83]
	v_mfma_f32_16x16x32_bf16 v[84:87], v[180:183], v[224:227], v[84:87]
	v_mfma_f32_16x16x32_bf16 v[88:91], v[184:187], v[224:227], v[88:91]
	v_mfma_f32_16x16x32_bf16 v[92:95], v[188:191], v[224:227], v[92:95]
	v_mfma_f32_16x16x32_bf16 v[96:99], v[176:179], v[228:231], v[96:99]
	v_mfma_f32_16x16x32_bf16 v[100:103], v[180:183], v[228:231], v[100:103]
	v_mfma_f32_16x16x32_bf16 v[104:107], v[184:187], v[228:231], v[104:107]
	v_mfma_f32_16x16x32_bf16 v[108:111], v[188:191], v[228:231], v[108:111]
	v_mfma_f32_16x16x32_bf16 v[112:115], v[176:179], v[232:235], v[112:115]
	v_mfma_f32_16x16x32_bf16 v[116:119], v[180:183], v[232:235], v[116:119]
	v_mfma_f32_16x16x32_bf16 v[120:123], v[184:187], v[232:235], v[120:123]
	v_mfma_f32_16x16x32_bf16 v[124:127], v[188:191], v[232:235], v[124:127]
	s_setprio 0
	s_nop 7
	v_cvt_pk_bf16_f32 v220, v0, v1
	v_cvt_pk_bf16_f32 v221, v2, v3
	v_cvt_pk_bf16_f32 v222, v4, v5
	v_cvt_pk_bf16_f32 v223, v6, v7
	v_cvt_pk_bf16_f32 v224, v8, v9
	v_cvt_pk_bf16_f32 v225, v10, v11
	v_cvt_pk_bf16_f32 v226, v12, v13
	v_cvt_pk_bf16_f32 v227, v14, v15
	global_store_dwordx2 v236, v[220:221], s[34:35] offset:0
	global_store_dwordx2 v236, v[222:223], s[34:35] offset:32
	global_store_dwordx2 v236, v[224:225], s[34:35] offset:64
	global_store_dwordx2 v236, v[226:227], s[34:35] offset:96
	s_add_u32 s34, s34, 0x1000
	s_addc_u32 s35, s35, 0
	v_cvt_pk_bf16_f32 v220, v16, v17
	v_cvt_pk_bf16_f32 v221, v18, v19
	v_cvt_pk_bf16_f32 v222, v20, v21
	v_cvt_pk_bf16_f32 v223, v22, v23
	v_cvt_pk_bf16_f32 v224, v24, v25
	v_cvt_pk_bf16_f32 v225, v26, v27
	v_cvt_pk_bf16_f32 v226, v28, v29
	v_cvt_pk_bf16_f32 v227, v30, v31
	global_store_dwordx2 v236, v[220:221], s[34:35] offset:0
	global_store_dwordx2 v236, v[222:223], s[34:35] offset:32
	global_store_dwordx2 v236, v[224:225], s[34:35] offset:64
	global_store_dwordx2 v236, v[226:227], s[34:35] offset:96
	s_add_u32 s34, s34, 0x1000
	s_addc_u32 s35, s35, 0
	v_cvt_pk_bf16_f32 v220, v32, v33
	v_cvt_pk_bf16_f32 v221, v34, v35
	v_cvt_pk_bf16_f32 v222, v36, v37
	v_cvt_pk_bf16_f32 v223, v38, v39
	v_cvt_pk_bf16_f32 v224, v40, v41
	v_cvt_pk_bf16_f32 v225, v42, v43
	v_cvt_pk_bf16_f32 v226, v44, v45
	v_cvt_pk_bf16_f32 v227, v46, v47
	global_store_dwordx2 v236, v[220:221], s[34:35] offset:0
	global_store_dwordx2 v236, v[222:223], s[34:35] offset:32
	global_store_dwordx2 v236, v[224:225], s[34:35] offset:64
	global_store_dwordx2 v236, v[226:227], s[34:35] offset:96
	s_add_u32 s34, s34, 0x1000
	s_addc_u32 s35, s35, 0
	v_cvt_pk_bf16_f32 v220, v48, v49
	v_cvt_pk_bf16_f32 v221, v50, v51
	v_cvt_pk_bf16_f32 v222, v52, v53
	v_cvt_pk_bf16_f32 v223, v54, v55
	v_cvt_pk_bf16_f32 v224, v56, v57
	v_cvt_pk_bf16_f32 v225, v58, v59
	v_cvt_pk_bf16_f32 v226, v60, v61
	v_cvt_pk_bf16_f32 v227, v62, v63
	global_store_dwordx2 v236, v[220:221], s[34:35] offset:0
	global_store_dwordx2 v236, v[222:223], s[34:35] offset:32
	global_store_dwordx2 v236, v[224:225], s[34:35] offset:64
	global_store_dwordx2 v236, v[226:227], s[34:35] offset:96
	s_add_u32 s34, s34, 0x1000
	s_addc_u32 s35, s35, 0
	v_cvt_pk_bf16_f32 v220, v64, v65
	v_cvt_pk_bf16_f32 v221, v66, v67
	v_cvt_pk_bf16_f32 v222, v68, v69
	v_cvt_pk_bf16_f32 v223, v70, v71
	v_cvt_pk_bf16_f32 v224, v72, v73
	v_cvt_pk_bf16_f32 v225, v74, v75
	v_cvt_pk_bf16_f32 v226, v76, v77
	v_cvt_pk_bf16_f32 v227, v78, v79
	global_store_dwordx2 v236, v[220:221], s[34:35] offset:0
	global_store_dwordx2 v236, v[222:223], s[34:35] offset:32
	global_store_dwordx2 v236, v[224:225], s[34:35] offset:64
	global_store_dwordx2 v236, v[226:227], s[34:35] offset:96
	s_add_u32 s34, s34, 0x1000
	s_addc_u32 s35, s35, 0
	v_cvt_pk_bf16_f32 v220, v80, v81
	v_cvt_pk_bf16_f32 v221, v82, v83
	v_cvt_pk_bf16_f32 v222, v84, v85
	v_cvt_pk_bf16_f32 v223, v86, v87
	v_cvt_pk_bf16_f32 v224, v88, v89
	v_cvt_pk_bf16_f32 v225, v90, v91
	v_cvt_pk_bf16_f32 v226, v92, v93
	v_cvt_pk_bf16_f32 v227, v94, v95
	global_store_dwordx2 v236, v[220:221], s[34:35] offset:0
	global_store_dwordx2 v236, v[222:223], s[34:35] offset:32
	global_store_dwordx2 v236, v[224:225], s[34:35] offset:64
	global_store_dwordx2 v236, v[226:227], s[34:35] offset:96
	s_add_u32 s34, s34, 0x1000
	s_addc_u32 s35, s35, 0
	v_cvt_pk_bf16_f32 v220, v96, v97
	v_cvt_pk_bf16_f32 v221, v98, v99
	v_cvt_pk_bf16_f32 v222, v100, v101
	v_cvt_pk_bf16_f32 v223, v102, v103
	v_cvt_pk_bf16_f32 v224, v104, v105
	v_cvt_pk_bf16_f32 v225, v106, v107
	v_cvt_pk_bf16_f32 v226, v108, v109
	v_cvt_pk_bf16_f32 v227, v110, v111
	global_store_dwordx2 v236, v[220:221], s[34:35] offset:0
	global_store_dwordx2 v236, v[222:223], s[34:35] offset:32
	global_store_dwordx2 v236, v[224:225], s[34:35] offset:64
	global_store_dwordx2 v236, v[226:227], s[34:35] offset:96
	s_add_u32 s34, s34, 0x1000
	s_addc_u32 s35, s35, 0
	v_cvt_pk_bf16_f32 v220, v112, v113
	v_cvt_pk_bf16_f32 v221, v114, v115
	v_cvt_pk_bf16_f32 v222, v116, v117
	v_cvt_pk_bf16_f32 v223, v118, v119
	v_cvt_pk_bf16_f32 v224, v120, v121
	v_cvt_pk_bf16_f32 v225, v122, v123
	v_cvt_pk_bf16_f32 v226, v124, v125
	v_cvt_pk_bf16_f32 v227, v126, v127
	global_store_dwordx2 v236, v[220:221], s[34:35] offset:0
	global_store_dwordx2 v236, v[222:223], s[34:35] offset:32
	global_store_dwordx2 v236, v[224:225], s[34:35] offset:64
	global_store_dwordx2 v236, v[226:227], s[34:35] offset:96
	s_add_u32 s34, s34, 0x1000
	s_addc_u32 s35, s35, 0
	s_sub_u32 s34, s34, 0x8000
	s_subb_u32 s35, s35, 0
	s_and_b32 s28, s29, 63
	s_lshl_b32 s28, s28, 20
	s_add_u32 s40, s94, s28
	s_addc_u32 s41, s95, 0
	s_add_u32 s40, s40, 0x15000000
	s_addc_u32 s41, s41, 0
	s_add_u32 s42, s40, 0x80000
	s_addc_u32 s43, s41, 0
	s_lshr_b32 s28, s29, 6
	s_lshl_b32 s28, s28, 19
	s_add_u32 s44, s94, s28
	s_addc_u32 s45, s95, 0
	s_add_u32 s44, s44, 0x1ca00000
	s_addc_u32 s45, s45, 0
	s_mov_b32 s46, 0xf80
	v_readlane_b32 s39, v242, 45
	s_and_b32 s39, s39, 7
	s_lshl_b32 s39, s39, 9
	s_and_b32 s39, s39, s46
	s_add_u32 s20, s40, s39
	s_addc_u32 s21, s41, 0
	s_add_u32 s22, s42, s39
	s_addc_u32 s23, s43, 0
	s_add_u32 s24, s44, s39
	s_addc_u32 s25, s45, 0
	s_barrier
	s_add_u32 m0, s26, 0x0
	s_nop 0
	global_load_lds_dwordx4 v244, s[20:21]
	s_add_u32 m0, s26, 0x1000
	s_nop 0
	global_load_lds_dwordx4 v245, s[20:21]
	s_add_u32 m0, s26, 0x2000
	s_nop 0
	global_load_lds_dwordx4 v246, s[20:21]
	s_add_u32 m0, s26, 0x3000
	s_nop 0
	global_load_lds_dwordx4 v247, s[20:21]
	s_add_u32 m0, s26, 0x4000
	s_nop 0
	global_load_lds_dwordx4 v244, s[22:23]
	s_add_u32 m0, s26, 0x5000
	s_nop 0
	global_load_lds_dwordx4 v245, s[22:23]
	s_add_u32 m0, s26, 0x6000
	s_nop 0
	global_load_lds_dwordx4 v246, s[22:23]
	s_add_u32 m0, s26, 0x7000
	s_nop 0
	global_load_lds_dwordx4 v247, s[22:23]
	s_add_u32 m0, s26, 0x8000
	s_nop 0
	global_load_lds_dwordx4 v244, s[24:25]
	s_add_u32 m0, s26, 0x9000
	s_nop 0
	global_load_lds_dwordx4 v245, s[24:25]
	s_add_u32 m0, s26, 0xa000
	s_nop 0
	global_load_lds_dwordx4 v246, s[24:25]
	s_add_u32 m0, s26, 0xb000
	s_nop 0
	global_load_lds_dwordx4 v247, s[24:25]
	s_add_u32 s39, s39, 0x80
	s_and_b32 s39, s39, s46
	s_add_u32 s20, s40, s39
	s_addc_u32 s21, s41, 0
	s_add_u32 s22, s42, s39
	s_addc_u32 s23, s43, 0
	s_add_u32 s24, s44, s39
	s_addc_u32 s25, s45, 0
	v_mov_b32_e32 v0, 0
	v_mov_b32_e32 v1, 0
	v_mov_b32_e32 v2, 0
	v_mov_b32_e32 v3, 0
	v_mov_b32_e32 v4, 0
	v_mov_b32_e32 v5, 0
	v_mov_b32_e32 v6, 0
	v_mov_b32_e32 v7, 0
	v_mov_b32_e32 v8, 0
	v_mov_b32_e32 v9, 0
	v_mov_b32_e32 v10, 0
	v_mov_b32_e32 v11, 0
	v_mov_b32_e32 v12, 0
	v_mov_b32_e32 v13, 0
	v_mov_b32_e32 v14, 0
	v_mov_b32_e32 v15, 0
	v_mov_b32_e32 v16, 0
	v_mov_b32_e32 v17, 0
	v_mov_b32_e32 v18, 0
	v_mov_b32_e32 v19, 0
	v_mov_b32_e32 v20, 0
	v_mov_b32_e32 v21, 0
	v_mov_b32_e32 v22, 0
	v_mov_b32_e32 v23, 0
	v_mov_b32_e32 v24, 0
	v_mov_b32_e32 v25, 0
	v_mov_b32_e32 v26, 0
	v_mov_b32_e32 v27, 0
	v_mov_b32_e32 v28, 0
	v_mov_b32_e32 v29, 0
	v_mov_b32_e32 v30, 0
	v_mov_b32_e32 v31, 0
	v_mov_b32_e32 v32, 0
	v_mov_b32_e32 v33, 0
	v_mov_b32_e32 v34, 0
	v_mov_b32_e32 v35, 0
	v_mov_b32_e32 v36, 0
	v_mov_b32_e32 v37, 0
	v_mov_b32_e32 v38, 0
	v_mov_b32_e32 v39, 0
	v_mov_b32_e32 v40, 0
	v_mov_b32_e32 v41, 0
	v_mov_b32_e32 v42, 0
	v_mov_b32_e32 v43, 0
	v_mov_b32_e32 v44, 0
	v_mov_b32_e32 v45, 0
	v_mov_b32_e32 v46, 0
	v_mov_b32_e32 v47, 0
	v_mov_b32_e32 v48, 0
	v_mov_b32_e32 v49, 0
	v_mov_b32_e32 v50, 0
	v_mov_b32_e32 v51, 0
	v_mov_b32_e32 v52, 0
	v_mov_b32_e32 v53, 0
	v_mov_b32_e32 v54, 0
	v_mov_b32_e32 v55, 0
	v_mov_b32_e32 v56, 0
	v_mov_b32_e32 v57, 0
	v_mov_b32_e32 v58, 0
	v_mov_b32_e32 v59, 0
	v_mov_b32_e32 v60, 0
	v_mov_b32_e32 v61, 0
	v_mov_b32_e32 v62, 0
	v_mov_b32_e32 v63, 0
	v_mov_b32_e32 v64, 0
	v_mov_b32_e32 v65, 0
	v_mov_b32_e32 v66, 0
	v_mov_b32_e32 v67, 0
	v_mov_b32_e32 v68, 0
	v_mov_b32_e32 v69, 0
	v_mov_b32_e32 v70, 0
	v_mov_b32_e32 v71, 0
	v_mov_b32_e32 v72, 0
	v_mov_b32_e32 v73, 0
	v_mov_b32_e32 v74, 0
	v_mov_b32_e32 v75, 0
	v_mov_b32_e32 v76, 0
	v_mov_b32_e32 v77, 0
	v_mov_b32_e32 v78, 0
	v_mov_b32_e32 v79, 0
	v_mov_b32_e32 v80, 0
	v_mov_b32_e32 v81, 0
	v_mov_b32_e32 v82, 0
	v_mov_b32_e32 v83, 0
	v_mov_b32_e32 v84, 0
	v_mov_b32_e32 v85, 0
	v_mov_b32_e32 v86, 0
	v_mov_b32_e32 v87, 0
	v_mov_b32_e32 v88, 0
	v_mov_b32_e32 v89, 0
	v_mov_b32_e32 v90, 0
	v_mov_b32_e32 v91, 0
	v_mov_b32_e32 v92, 0
	v_mov_b32_e32 v93, 0
	v_mov_b32_e32 v94, 0
	v_mov_b32_e32 v95, 0
	v_mov_b32_e32 v96, 0
	v_mov_b32_e32 v97, 0
	v_mov_b32_e32 v98, 0
	v_mov_b32_e32 v99, 0
	v_mov_b32_e32 v100, 0
	v_mov_b32_e32 v101, 0
	v_mov_b32_e32 v102, 0
	v_mov_b32_e32 v103, 0
	v_mov_b32_e32 v104, 0
	v_mov_b32_e32 v105, 0
	v_mov_b32_e32 v106, 0
	v_mov_b32_e32 v107, 0
	v_mov_b32_e32 v108, 0
	v_mov_b32_e32 v109, 0
	v_mov_b32_e32 v110, 0
	v_mov_b32_e32 v111, 0
	v_mov_b32_e32 v112, 0
	v_mov_b32_e32 v113, 0
	v_mov_b32_e32 v114, 0
	v_mov_b32_e32 v115, 0
	v_mov_b32_e32 v116, 0
	v_mov_b32_e32 v117, 0
	v_mov_b32_e32 v118, 0
	v_mov_b32_e32 v119, 0
	v_mov_b32_e32 v120, 0
	v_mov_b32_e32 v121, 0
	v_mov_b32_e32 v122, 0
	v_mov_b32_e32 v123, 0
	v_mov_b32_e32 v124, 0
	v_mov_b32_e32 v125, 0
	v_mov_b32_e32 v126, 0
	v_mov_b32_e32 v127, 0
	s_mov_b32 s27, 0
